# G1: half of the workgroups (blockIdx bit 3) start 5x s_sleep 127 later to de-synchronise tile epilogues / B-tile switches
# speedup vs baseline: 1.0350x; 1.0017x over previous
; #define PG8_STAGE(bufoff, gbase, voff) do { const char* _gb = (const char*)(gbase); asm volatile("" : "+s"(_gb)); _Pragma("unroll") for (int _i = 0; _i < 2; ++_i) \
;         __builtin_amdgcn_global_load_lds((const unsigned*)(_gb + (voff)[_i]), (LAS unsigned*)(lds + (bufoff) + ldsw + _i * 8192), 16, 0, 0); } while (0)
; #define PG8_BAR __builtin_amdgcn_s_barrier()
; template <class Epi, class Sched>
; __device__ __forceinline__ void gemm_phase(LAS unsigned char* lds, const Gemm g, const Sched& S, const Epi& E) {
;     ...
;     for (int i = 0; i < 2; ++i) { int R, C; stage_rc(tid * 16 + i * 8192, R, C); const int Rb = Epi::PERM ? ((R & ~31) + perm32(R & 31)) : R;
;         voffA[i] = (unsigned)(R * lda + C) * 2u; voffB[i] = (unsigned)(Rb * K + C) * 2u; }
;     const size_t kstep = (size_t)(BK * 2);
;     const size_t hA = (size_t)HALF * lda * 2, hB = (size_t)HALF * K * 2;
;     const size_t tA = 2 * hA, tB = 2 * hB;
;     const unsigned ldsw = (unsigned)wid * 1024u;
;     const int aoff = lds_byte(wr * 64 + fr, fq * 8), boff = lds_byte(wc * 32 + fr, fq * 8);
;     ...
;     const char* cA = (const char*)g.A + (size_t)cur.pm * tA; const char* cB = (const char*)g.Bt + (size_t)cur.pn * tB;
;     PG8_STAGE(PG8_SB(0, 0), cB, voffB); PG8_STAGE(PG8_SA(0, 0), cA, voffA); PG8_STAGE(PG8_SB(0, 1), cB + hB, voffB); PG8_STAGE(PG8_SA(0, 1), cA + hA, voffA);
;     if (wr == 1) PG8_BAR;
.LBB0_69:
	s_cmp_lt_i32 s80, 2
	s_cselect_b64 s[0:1], -1, 0
	s_and_b64 s[4:5], s[0:1], s[8:9]
	s_andn2_b64 vcc, exec, s[4:5]
	s_cbranch_vccnz .LBB0_79
	s_bitcmp1_b32 s2, 3
	s_cbranch_scc0 .Lg1_nodelay
	s_movk_i32 s3, 5
.Lg1_delay:
	s_sleep 127
	s_add_i32 s3, s3, -1
	s_cmp_lg_u32 s3, 0
	s_cbranch_scc1 .Lg1_delay
.Lg1_nodelay:
	v_mov_b32_e32 v0, v176
	s_mov_b32 s3, 0x1fffe0
	v_lshlrev_b32_e32 v1, 4, v0
	v_add_u32_e32 v2, 0x2000, v1
	v_ashrrev_i32_e32 v3, 31, v2
	v_lshrrev_b32_e32 v3, 22, v3
	v_add_u32_e32 v3, v2, v3
	v_ashrrev_i32_e32 v3, 10, v3
	v_mul_i32_i24_e32 v4, 0x400, v3
	v_sub_u32_e32 v2, v2, v4
	v_lshrrev_b32_e32 v4, 4, v2
	v_bitop3_b32 v2, v4, v2, 32 bitop3:0x6c
	v_ashrrev_i32_e32 v4, 31, v2
	v_lshrrev_b32_e32 v4, 26, v4
	v_add_u32_e32 v4, v2, v4
	v_lshlrev_b32_e32 v6, 3, v3
	v_ashrrev_i32_e32 v5, 6, v4
	v_and_b32_e32 v6, -16, v6
	v_and_b32_e32 v4, 0xc0, v4
	v_add_u32_e32 v6, v5, v6
	v_sub_u32_e32 v2, v2, v4
	v_mov_b32_e32 v4, 1
	v_and_b32_e32 v5, 3, v5
	v_lshrrev_b32_e32 v7, 2, v6
	v_lshlrev_b32_e32 v8, 1, v6
	v_lshlrev_b32_e32 v3, 5, v3
	v_ashrrev_i16_sdwa v2, v4, sext(v2) dst_sel:DWORD dst_unused:UNUSED_PAD src0_sel:DWORD src1_sel:BYTE_0
	v_and_or_b32 v5, v6, s3, v5
	v_and_b32_e32 v7, 4, v7
	v_and_b32_e32 v8, 24, v8
	v_and_b32_e32 v3, 32, v3
	v_bfe_i32 v2, v2, 0, 16
	v_or3_b32 v5, v5, v7, v8
	v_add_lshl_u32 v2, v3, v2, 1
	v_lshl_add_u32 v128, v5, 11, v2
	v_lshl_add_u32 v130, v6, 11, v2
	v_bfe_i32 v2, v0, 27, 1
	v_lshrrev_b32_e32 v2, 22, v2
	v_add_u32_e32 v2, v1, v2
	v_and_b32_e32 v2, 0xfffffc00, v2
	v_sub_u32_e32 v1, v1, v2
	v_lshrrev_b32_e32 v2, 4, v1
	v_ashrrev_i32_e32 v5, 31, v0
	v_bitop3_b32 v1, v2, v1, 32 bitop3:0x6c
	v_lshrrev_b32_e32 v5, 26, v5
	v_ashrrev_i32_e32 v2, 31, v1
	v_add_u32_e32 v5, v0, v5
	v_lshrrev_b32_e32 v2, 26, v2
	v_ashrrev_i32_e32 v5, 6, v5
	v_add_u32_e32 v2, v1, v2
	v_lshlrev_b32_e32 v6, 3, v5
	v_ashrrev_i32_e32 v3, 6, v2
	v_and_b32_e32 v6, -16, v6
	v_and_b32_e32 v2, 0xc0, v2
	s_add_u32 s4, s78, 0x18000000
	v_readfirstlane_b32 s20, v0
	v_add_u32_e32 v6, v3, v6
	v_sub_u32_e32 v1, v1, v2
	s_addc_u32 s5, s79, 0
	s_ashr_i32 s9, s20, 6
	v_and_b32_e32 v3, 3, v3
	v_lshrrev_b32_e32 v7, 2, v6
	v_lshlrev_b32_e32 v8, 1, v6
	v_lshlrev_b32_e32 v5, 5, v5
	v_ashrrev_i16_sdwa v1, v4, sext(v1) dst_sel:DWORD dst_unused:UNUSED_PAD src0_sel:DWORD src1_sel:BYTE_0
	s_lshl_b32 s21, s9, 10
	v_and_or_b32 v3, v6, s3, v3
	v_and_b32_e32 v7, 4, v7
	v_and_b32_e32 v8, 24, v8
	v_and_b32_e32 v5, 32, v5
	v_bfe_i32 v1, v1, 0, 16
	s_ashr_i32 s3, s2, 31
	v_or3_b32 v3, v3, v7, v8
	v_add_lshl_u32 v1, v5, v1, 1
	s_lshl_b64 s[6:7], s[2:3], 19
	s_add_i32 s3, s21, 0
	v_lshl_add_u32 v132, v3, 11, v1
	s_mov_b64 s[10:11], s[4:5]
	s_add_i32 m0, s3, 0x10000
	s_ashr_i32 s8, s20, 8
	v_lshl_add_u32 v134, v6, 11, v1
	global_load_lds_dwordx4 v132, s[10:11]
	s_add_i32 m0, s3, 0x12000
	s_add_u32 s6, s76, s6
	s_addc_u32 s7, s77, s7
	global_load_lds_dwordx4 v128, s[10:11]
	s_mov_b64 s[10:11], s[6:7]
	s_mov_b32 m0, s3
	s_add_i32 s22, s3, 0x2000
	v_mov_b32_e32 v137, 0
	global_load_lds_dwordx4 v134, s[10:11]
	s_mov_b32 m0, s22
	s_mov_b32 s38, 0
	global_load_lds_dwordx4 v130, s[10:11]
	s_add_u32 s10, s78, 0x18040000
	s_addc_u32 s11, s79, 0
	s_add_i32 m0, s3, 0x14000
	v_mov_b32_e32 v133, v137
	global_load_lds_dwordx4 v132, s[10:11]
	s_add_i32 m0, s3, 0x16000
	v_mov_b32_e32 v129, v137
	global_load_lds_dwordx4 v128, s[10:11]
	s_add_u32 s10, s6, 0x40000
	s_addc_u32 s11, s7, 0
	s_add_i32 s23, s3, 0x4000
	s_mov_b32 m0, s23
	s_add_i32 s24, s3, 0x6000
	v_mov_b32_e32 v135, v137
	global_load_lds_dwordx4 v134, s[10:11]
	s_mov_b32 m0, s24
	s_cmp_lg_u32 s8, 1
	global_load_lds_dwordx4 v130, s[10:11]
	v_mov_b32_e32 v131, v137
	s_cbranch_scc1 .LBB0_72
	s_barrier
